# v36 + attention tile loop: the 8 LDS-DMA issues in SGPR-base (saddr) form, no 64-bit VALU address adds
# speedup vs baseline: 1.0096x; 1.0096x over previous
; template <int D0, int S> __device__ __forceinline__ VG vload(ldsc_t vb) { VG g; g.l0 = vtr(vb + v_rd_off(D0, 2 * S, 0)); g.h0 = vtr(vb + v_rd_off(D0, 2 * S, 1)); g.l1 = vtr(vb + v_rd_off(D0, 2 * S + 1, 0)); g.h1 = vtr(vb + v_rd_off(D0, 2 * S + 1, 1)); return g; }
; #define DMA_K1(g_, b, i_) __builtin_amdgcn_global_load_lds((const unsigned*)((g_) + (((i_) & 1) * 32 * LD * 2 + ((i_) >> 1) * 256) + koff0), (__attribute__((address_space(3))) unsigned*)(ldsb + (b) * STAGE + (wid + 8 * (i_)) * 1024), 16, 0, 0)
; __device__ __forceinline__ void softmax_sub(f32x16& p, float& m_reg, float& l_reg, bf16x8& pa0, bf16x8& pa1, f32x16 (&o)[8], float* al_l, int r32, int hi, int dj, const float* tab, float cL, float cR) {
;     ...
;   if (dj <= -159) cb = cL;
;   else if (dj >= 159) cb = cR;
;   else { cb = 0.f; const int ib = dj - r32 + 4 * hi + 128;
; #pragma unroll
;     for (int r = 0; r < 16; ++r) { const int i0 = ib + (r & 3) + 8 * (r >> 2); p[r] += tab[min(max(i0, 0), 256)]; } }
; __device__ __forceinline__ void attn_unit(const bf16* __restrict__ qkvb, int seq, int q0, int h, ldsp_t ldsb, float* wsc, const float* tab, float lam) {
;     ...
;     const int bo = (j & 1) * STAGE; const int bn = (j + 1) & 1; const bool more = j + 1 < NT;
;     const char* gn = kvb + (long)(j + 1) * tstep;
;     asm volatile("s_waitcnt vmcnt(0)" ::: "memory");
;     asm volatile("" ::: "memory"); __builtin_amdgcn_s_barrier(); asm volatile("" ::: "memory");
;     {
;       f32x16 p0, p1; bf16x8 pa0, pa1;
;       qk_sub(p0, kp[0] + bo, kp[1] + bo, kp[2] + bo, kp[3] + bo, kd, qr, [&](int i) { if (more) DMA_K1(gn, bn, i); });
;       qk_sub(p1, kp[0] + bo + 8192, kp[1] + bo + 8192, kp[2] + bo + 8192, kp[3] + bo + 8192, kd, qr, [](int) {});
;       { VG g0 = vload<0, 0>(vp + bo), g1 = vload<1, 0>(vp + bo);
.LBB0_548:
	s_waitcnt vmcnt(0)
	s_add_i32 s4, s27, 0xffff0000
	s_barrier
	s_and_b32 s29, s4, 0x10000
	v_add_u32_e32 v1, s29, v252
	v_add_u32_e32 v198, s29, v253
	v_add_u32_e32 v199, s29, v241
	v_add_u32_e32 v202, s29, v244
	ds_read_b128 v[130:133], v1
	ds_read_b128 v[134:137], v198
	ds_read_b128 v[138:141], v199
	ds_read_b128 v[142:145], v202
	s_setprio 1
	s_waitcnt lgkmcnt(0)
	v_mfma_f32_32x32x16_bf16 v[146:161], v[130:133], v[190:193], 0
	v_add_u32_e32 v206, v1, v251
	ds_read_b128 v[130:133], v206
	s_and_b32 s24, s27, 0x10000
	s_add_i32 s28, s23, s24
	v_add_u32_e32 v210, v198, v251
	v_mfma_f32_32x32x16_bf16 v[146:161], v[134:137], v[186:189], v[146:161]
	ds_read_b128 v[134:137], v210
	s_add_u32 s4, s8, 0xc0000
	s_addc_u32 s5, s9, 0
	s_mov_b32 m0, s28
	s_nop 0
	global_load_lds_dwordx4 v226, s[4:5]
	v_mfma_f32_32x32x16_bf16 v[146:161], v[138:141], v[182:185], v[146:161]
	v_add_u32_e32 v212, v199, v251
	ds_read_b128 v[138:141], v212
	v_add_u32_e32 v213, v202, v251
	v_mfma_f32_32x32x16_bf16 v[146:161], v[142:145], v[178:181], v[146:161]
	ds_read_b128 v[142:145], v213
	s_add_u32 s4, s8, 0x120000
	s_addc_u32 s5, s9, 0
	s_add_i32 m0, s28, 0x2000
	s_nop 0
	global_load_lds_dwordx4 v226, s[4:5]
	s_waitcnt lgkmcnt(0)
	v_mfma_f32_32x32x16_bf16 v[146:161], v[130:133], v[174:177], v[146:161]
	s_add_u32 s4, s8, 0xc0100
	s_addc_u32 s5, s9, 0
	s_add_i32 m0, s28, 0x4000
	s_nop 0
	global_load_lds_dwordx4 v226, s[4:5]
	v_mfma_f32_32x32x16_bf16 v[146:161], v[134:137], v[170:173], v[146:161]
	v_mfma_f32_32x32x16_bf16 v[146:161], v[138:141], v[166:169], v[146:161]
	s_add_u32 s4, s8, 0x120100
	s_addc_u32 s5, s9, 0
	s_add_i32 m0, s28, 0x6000
	s_nop 0
	global_load_lds_dwordx4 v226, s[4:5]
	v_mfma_f32_32x32x16_bf16 v[146:161], v[142:145], v[162:165], v[146:161]
	s_setprio 0
	ds_read_b128 v[130:133], v1 offset:8192
	ds_read_b128 v[194:197], v198 offset:8192
	ds_read_b128 v[198:201], v199 offset:8192
	ds_read_b128 v[202:205], v202 offset:8192
	s_setprio 1
	s_waitcnt lgkmcnt(0)
	v_mfma_f32_32x32x16_bf16 v[130:145], v[130:133], v[190:193], 0
	ds_read_b128 v[206:209], v206 offset:8192
	v_mfma_f32_32x32x16_bf16 v[130:145], v[194:197], v[186:189], v[130:145]
	ds_read_b128 v[194:197], v210 offset:8192
	v_mfma_f32_32x32x16_bf16 v[130:145], v[198:201], v[182:185], v[130:145]
	ds_read_b128 v[198:201], v212 offset:8192
	v_mfma_f32_32x32x16_bf16 v[130:145], v[202:205], v[178:181], v[130:145]
	ds_read_b128 v[202:205], v213 offset:8192
	s_waitcnt lgkmcnt(0)
	v_mfma_f32_32x32x16_bf16 v[130:145], v[206:209], v[174:177], v[130:145]
	v_mfma_f32_32x32x16_bf16 v[130:145], v[194:197], v[170:173], v[130:145]
	v_mfma_f32_32x32x16_bf16 v[130:145], v[198:201], v[166:169], v[130:145]
	v_mfma_f32_32x32x16_bf16 v[130:145], v[202:205], v[162:165], v[130:145]
	s_setprio 0
	v_add_u32_e32 v1, s29, v250
	ds_read_b64_tr_b16 v[206:207], v1 offset:32768
	ds_read_b64_tr_b16 v[208:209], v1 offset:36864
	ds_read_b64_tr_b16 v[200:201], v1 offset:37376
	ds_read_b64_tr_b16 v[198:199], v1 offset:33280
	ds_read_b64_tr_b16 v[202:203], v1 offset:40960
	ds_read_b64_tr_b16 v[204:205], v1 offset:45056
	ds_read_b64_tr_b16 v[196:197], v1 offset:45568
	ds_read_b64_tr_b16 v[194:195], v1 offset:41472
	s_cmpk_lt_i32 s26, 0xff62
	s_cbranch_scc1 .LBB0_551
	s_cmpk_gt_i32 s26, 0x9e
	s_cbranch_scc1 .LBB0_552
	v_add_u32_e32 v210, s26, v245
	v_add_u32_e32 v210, 0x80, v210
	v_mov_b32_e32 v212, 0x100
	v_med3_i32 v212, v210, 0, v212
	v_lshl_add_u32 v220, v212, 2, s20
	v_max_i32_e32 v212, -1, v210
	v_add_u32_e32 v212, 1, v212
	v_min_u32_e32 v212, 0x100, v212
	v_lshl_add_u32 v221, v212, 2, s20
	v_max_i32_e32 v212, -2, v210
	v_add_u32_e32 v212, 2, v212
	v_min_u32_e32 v212, 0x100, v212
	v_lshl_add_u32 v222, v212, 2, s20
	v_max_i32_e32 v212, -3, v210
	v_add_u32_e32 v212, 3, v212
	v_min_u32_e32 v212, 0x100, v212
	v_lshl_add_u32 v223, v212, 2, s20
	v_max_i32_e32 v212, -8, v210
	v_add_u32_e32 v212, 8, v212
	v_min_u32_e32 v212, 0x100, v212
	v_lshl_add_u32 v224, v212, 2, s20
	v_max_i32_e32 v212, -9, v210
	v_add_u32_e32 v212, 9, v212
	v_min_u32_e32 v212, 0x100, v212
	v_lshl_add_u32 v225, v212, 2, s20
	v_max_i32_e32 v212, -10, v210
	v_add_u32_e32 v212, 10, v212
	v_min_u32_e32 v212, 0x100, v212
	v_lshl_add_u32 v232, v212, 2, s20
	v_max_i32_e32 v212, -11, v210
	v_add_u32_e32 v212, 11, v212
	v_min_u32_e32 v212, 0x100, v212
	v_lshl_add_u32 v233, v212, 2, s20
	v_max_i32_e32 v212, -16, v210
	v_max_i32_e32 v213, 0xffffffef, v210
	v_max_i32_e32 v214, 0xffffffee, v210
	v_max_i32_e32 v215, 0xffffffed, v210
	v_max_i32_e32 v216, 0xffffffe8, v210
	v_max_i32_e32 v217, 0xffffffe7, v210
	v_max_i32_e32 v218, 0xffffffe6, v210
	v_add_u32_e32 v212, 16, v212
	v_add_u32_e32 v213, 17, v213
	v_add_u32_e32 v214, 18, v214
	v_add_u32_e32 v215, 19, v215
	v_add_u32_e32 v216, 24, v216
	v_add_u32_e32 v217, 25, v217
	v_add_u32_e32 v218, 26, v218
	v_max_i32_e32 v210, 0xffffffe5, v210
	v_min_u32_e32 v212, 0x100, v212
	v_min_u32_e32 v213, 0x100, v213
	v_min_u32_e32 v214, 0x100, v214
	v_min_u32_e32 v215, 0x100, v215
	v_min_u32_e32 v216, 0x100, v216
	v_min_u32_e32 v217, 0x100, v217
	v_min_u32_e32 v218, 0x100, v218
	v_add_u32_e32 v210, 27, v210
	v_lshl_add_u32 v212, v212, 2, s20
	v_lshl_add_u32 v213, v213, 2, s20
	v_lshl_add_u32 v214, v214, 2, s20
	v_lshl_add_u32 v215, v215, 2, s20
	v_lshl_add_u32 v216, v216, 2, s20
	v_lshl_add_u32 v217, v217, 2, s20
	v_lshl_add_u32 v218, v218, 2, s20
	v_min_u32_e32 v210, 0x100, v210
	v_lshl_add_u32 v210, v210, 2, s20
	ds_read_b32 v212, v212
	ds_read_b32 v213, v213
	ds_read_b32 v214, v214
	ds_read_b32 v215, v215
	ds_read_b32 v216, v216
	ds_read_b32 v217, v217
	ds_read_b32 v218, v218
	ds_read_b32 v219, v210
	ds_read_b32 v220, v220
	ds_read_b32 v221, v221
	ds_read_b32 v222, v222
	ds_read_b32 v223, v223
	ds_read_b32 v224, v224
	ds_read_b32 v225, v225
	ds_read_b32 v232, v232
	ds_read_b32 v233, v233
	s_waitcnt lgkmcnt(0)
	v_pk_add_f32 v[160:161], v[160:161], v[218:219]
	v_pk_add_f32 v[158:159], v[158:159], v[216:217]
	v_pk_add_f32 v[156:157], v[156:157], v[214:215]
	v_pk_add_f32 v[154:155], v[154:155], v[212:213]
	v_pk_add_f32 v[152:153], v[152:153], v[232:233]
	v_pk_add_f32 v[150:151], v[150:151], v[224:225]
	v_pk_add_f32 v[148:149], v[148:149], v[222:223]
	v_pk_add_f32 v[146:147], v[146:147], v[220:221]
	s_mov_b32 s29, 0
	s_branch .LBB0_553

; #define SBAR() __builtin_amdgcn_sched_barrier(0)
; template <int D0, int S> __device__ __forceinline__ VG vload(ldsc_t vb) { VG g; g.l0 = vtr(vb + v_rd_off(D0, 2 * S, 0)); g.h0 = vtr(vb + v_rd_off(D0, 2 * S, 1)); g.l1 = vtr(vb + v_rd_off(D0, 2 * S + 1, 0)); g.h1 = vtr(vb + v_rd_off(D0, 2 * S + 1, 1)); return g; }
; __device__ __forceinline__ void softmax_sub(f32x16& p, float& m_reg, float& l_reg, bf16x8& pa0, bf16x8& pa1, f32x16 (&o)[8], float* al_l, int r32, int hi, int dj, const float* tab, float cL, float cR) {
;     ...
;   const float mnC = (cb - mn) * C;
;   float ps = 0;
; #pragma unroll
;   for (int r = 0; r < 16; ++r) { p[r] = __builtin_amdgcn_exp2f(fmaf(p[r], C, mnC)); ps += p[r]; }
;   { auto rr = __builtin_amdgcn_permlane32_swap(__float_as_uint(ps), __float_as_uint(ps), false, false);
;     ps = __uint_as_float(rr[0]) + __uint_as_float(rr[1]); }
;   l_reg = l_reg * alpha + ps;
;     ...
;   PK4(p, 0, pa0); PK4(p, 8, pa1);
;     ...
; }
; template <int S, class Dma> __device__ __forceinline__ void pv_run(f32x16 (&o)[8], ldsc_t vb, VG g0, VG g1, bf16x8 pa0, bf16x8 pa1, const Dma& dma) {
;   SBAR(); __builtin_amdgcn_s_setprio(1);
;   vmma(o[0], g0, pa0, pa1); dma(0); SBAR(); g0 = vload<2, S>(vb); SBAR();
;   vmma(o[1], g1, pa0, pa1); dma(1); SBAR(); g1 = vload<3, S>(vb); SBAR();
;   vmma(o[2], g0, pa0, pa1); dma(2); SBAR(); g0 = vload<4, S>(vb); SBAR();
;   vmma(o[3], g1, pa0, pa1); dma(3); SBAR(); g1 = vload<5, S>(vb); SBAR();
;   vmma(o[4], g0, pa0, pa1); dma(4); SBAR(); g0 = vload<6, S>(vb); SBAR();
;   vmma(o[5], g1, pa0, pa1); dma(5); SBAR(); g1 = vload<7, S>(vb); SBAR();
;   vmma(o[6], g0, pa0, pa1); dma(6); SBAR(); vmma(o[7], g1, pa0, pa1); dma(7); __builtin_amdgcn_s_setprio(0); SBAR();
.LBB0_555:
	v_sub_f32_e32 v211, s29, v210
	v_mul_f32_e32 v211, 0x3e0293ee, v211
	v_fmamk_f32 v146, v146, 0x3e0293ee, v211
	v_exp_f32_e32 v146, v146
	v_fmamk_f32 v147, v147, 0x3e0293ee, v211
	v_exp_f32_e32 v147, v147
	v_fmamk_f32 v148, v148, 0x3e0293ee, v211
	v_exp_f32_e32 v148, v148
	v_fmamk_f32 v149, v149, 0x3e0293ee, v211
	v_exp_f32_e32 v149, v149
	v_fmamk_f32 v150, v150, 0x3e0293ee, v211
	v_add_f32_e32 v212, 0, v146
	v_exp_f32_e32 v150, v150
	v_fmamk_f32 v151, v151, 0x3e0293ee, v211
	v_add_f32_e32 v212, v147, v212
	v_exp_f32_e32 v151, v151
	v_fmamk_f32 v152, v152, 0x3e0293ee, v211
	v_add_f32_e32 v212, v148, v212
	v_exp_f32_e32 v152, v152
	v_fmamk_f32 v153, v153, 0x3e0293ee, v211
	v_add_f32_e32 v212, v149, v212
	v_exp_f32_e32 v153, v153
	v_fmamk_f32 v154, v154, 0x3e0293ee, v211
	v_add_f32_e32 v212, v150, v212
	v_exp_f32_e32 v154, v154
	v_fmamk_f32 v155, v155, 0x3e0293ee, v211
	v_add_f32_e32 v212, v151, v212
	v_exp_f32_e32 v155, v155
	v_fmamk_f32 v156, v156, 0x3e0293ee, v211
	v_add_f32_e32 v212, v152, v212
	v_exp_f32_e32 v156, v156
	v_fmamk_f32 v157, v157, 0x3e0293ee, v211
	v_add_f32_e32 v212, v153, v212
	v_exp_f32_e32 v157, v157
	v_fmamk_f32 v158, v158, 0x3e0293ee, v211
	v_add_f32_e32 v212, v154, v212
	v_exp_f32_e32 v158, v158
	v_fmamk_f32 v159, v159, 0x3e0293ee, v211
	v_add_f32_e32 v212, v155, v212
	v_exp_f32_e32 v159, v159
	v_fmamk_f32 v160, v160, 0x3e0293ee, v211
	v_add_f32_e32 v212, v156, v212
	v_exp_f32_e32 v160, v160
	v_fmac_f32_e32 v211, 0x3e0293ee, v161
	v_add_f32_e32 v212, v157, v212
	v_exp_f32_e32 v161, v211
	v_add_f32_e32 v211, v158, v212
	v_add_f32_e32 v211, v159, v211
	v_add_f32_e32 v211, v160, v211
	v_add_f32_e32 v212, v161, v211
	v_mov_b32_e32 v213, v212
	v_cvt_pk_bf16_f32 v146, v146, v147
	v_cvt_pk_bf16_f32 v147, v148, v149
	v_cvt_pk_bf16_f32 v148, v150, v151
	v_cvt_pk_bf16_f32 v149, v152, v153
	v_cvt_pk_bf16_f32 v150, v154, v155
	v_cvt_pk_bf16_f32 v151, v156, v157
	v_cvt_pk_bf16_f32 v152, v158, v159
	v_cvt_pk_bf16_f32 v153, v160, v161
	s_nop 1
	v_permlane32_swap_b32_e32 v212, v213
	v_permlane32_swap_b32_e32 v146, v148
	v_permlane32_swap_b32_e32 v147, v149
	v_permlane32_swap_b32_e32 v150, v152
	v_permlane32_swap_b32_e32 v151, v153
	s_setprio 1
	s_waitcnt lgkmcnt(0)
	v_mfma_f32_32x32x16_bf16 v[98:113], v[146:149], v[206:209], v[98:113]
	s_add_u32 s4, s8, 0xc0000
	s_addc_u32 s5, s9, 0
	s_add_i32 m0, s28, 0x8000
	s_nop 0
	global_load_lds_dwordx4 v238, s[4:5]
	v_mfma_f32_32x32x16_bf16 v[98:113], v[150:153], v[202:205], v[98:113]
	ds_read_b64_tr_b16 v[154:155], v1 offset:33792
	ds_read_b64_tr_b16 v[156:157], v1 offset:37888
	ds_read_b64_tr_b16 v[158:159], v1 offset:41984
	ds_read_b64_tr_b16 v[160:161], v1 offset:46080
	v_mfma_f32_32x32x16_bf16 v[114:129], v[146:149], v[198:201], v[114:129]
	s_add_u32 s4, s8, 0xf0000
	s_addc_u32 s5, s9, 0
	s_add_i32 m0, s28, 0xa000
	s_nop 0
	global_load_lds_dwordx4 v238, s[4:5]
	v_mfma_f32_32x32x16_bf16 v[114:129], v[150:153], v[194:197], v[114:129]
	ds_read_b64_tr_b16 v[194:195], v1 offset:34304
	ds_read_b64_tr_b16 v[196:197], v1 offset:38400
	ds_read_b64_tr_b16 v[198:199], v1 offset:42496
	ds_read_b64_tr_b16 v[200:201], v1 offset:46592
	s_waitcnt lgkmcnt(0)
	v_mfma_f32_32x32x16_bf16 v[66:81], v[146:149], v[154:157], v[66:81]
	s_add_u32 s4, s8, 0x120000
	s_addc_u32 s5, s9, 0
	s_add_i32 m0, s28, 0xc000
	s_nop 0
	global_load_lds_dwordx4 v238, s[4:5]
	v_mfma_f32_32x32x16_bf16 v[66:81], v[150:153], v[158:161], v[66:81]
	ds_read_b64_tr_b16 v[154:155], v1 offset:34816
	ds_read_b64_tr_b16 v[156:157], v1 offset:38912
	ds_read_b64_tr_b16 v[158:159], v1 offset:43008
	ds_read_b64_tr_b16 v[160:161], v1 offset:47104
	v_mfma_f32_32x32x16_bf16 v[82:97], v[146:149], v[194:197], v[82:97]
	s_add_u32 s4, s8, 0x150000
	s_addc_u32 s5, s9, 0
	s_add_i32 m0, s28, 0xe000
	s_nop 0
	global_load_lds_dwordx4 v238, s[4:5]
	v_mfma_f32_32x32x16_bf16 v[82:97], v[150:153], v[198:201], v[82:97]
	ds_read_b64_tr_b16 v[194:195], v1 offset:35328
	ds_read_b64_tr_b16 v[196:197], v1 offset:39424
	ds_read_b64_tr_b16 v[198:199], v1 offset:43520
	ds_read_b64_tr_b16 v[200:201], v1 offset:47616
	s_waitcnt lgkmcnt(0)
	v_mfma_f32_32x32x16_bf16 v[34:49], v[146:149], v[154:157], v[34:49]
	v_mfma_f32_32x32x16_bf16 v[34:49], v[150:153], v[158:161], v[34:49]
	ds_read_b64_tr_b16 v[154:155], v1 offset:35840
	ds_read_b64_tr_b16 v[156:157], v1 offset:39936
	ds_read_b64_tr_b16 v[158:159], v1 offset:44032
	ds_read_b64_tr_b16 v[160:161], v1 offset:48128
	v_mfma_f32_32x32x16_bf16 v[50:65], v[146:149], v[194:197], v[50:65]
	v_mfma_f32_32x32x16_bf16 v[50:65], v[150:153], v[198:201], v[50:65]
	ds_read_b64_tr_b16 v[194:195], v1 offset:36352
	ds_read_b64_tr_b16 v[196:197], v1 offset:40448
	ds_read_b64_tr_b16 v[198:199], v1 offset:44544
	ds_read_b64_tr_b16 v[200:201], v1 offset:48640
	s_waitcnt lgkmcnt(0)
	v_mfma_f32_32x32x16_bf16 v[18:33], v[146:149], v[154:157], v[18:33]
	v_mfma_f32_32x32x16_bf16 v[18:33], v[150:153], v[158:161], v[18:33]
	v_mfma_f32_32x32x16_bf16 v[2:17], v[146:149], v[194:197], v[2:17]
	v_mfma_f32_32x32x16_bf16 v[2:17], v[150:153], v[198:201], v[2:17]
	s_setprio 0
	ds_read_b64_tr_b16 v[154:155], v1 offset:49152
	ds_read_b64_tr_b16 v[156:157], v1 offset:53248
	ds_read_b64_tr_b16 v[152:153], v1 offset:53760
	ds_read_b64_tr_b16 v[150:151], v1 offset:49664
	ds_read_b64_tr_b16 v[158:159], v1 offset:57344
	ds_read_b64_tr_b16 v[160:161], v1 offset:61440
	ds_read_b64_tr_b16 v[148:149], v1 offset:61952
	ds_read_b64_tr_b16 v[146:147], v1 offset:57856
	s_add_i32 s4, s26, 32
	s_cmpk_lt_i32 s4, 0xff62
	s_cbranch_scc1 .LBB0_558
; __device__ __forceinline__ void softmax_sub(f32x16& p, float& m_reg, float& l_reg, bf16x8& pa0, bf16x8& pa1, f32x16 (&o)[8], float* al_l, int r32, int hi, int dj, const float* tab, float cL, float cR) {
;     ...
;   if (dj <= -159) cb = cL;
;   else if (dj >= 159) cb = cR;
;   else { cb = 0.f; const int ib = dj - r32 + 4 * hi + 128;
; #pragma unroll
;     for (int r = 0; r < 16; ++r) { const int i0 = ib + (r & 3) + 8 * (r >> 2); p[r] += tab[min(max(i0, 0), 256)]; } }
	s_cmpk_gt_i32 s4, 0x9e
	s_cbranch_scc1 .LBB0_559
	v_add_u32_e32 v194, s26, v245
	v_add_u32_e32 v194, 0xa0, v194
	v_mov_b32_e32 v195, 0x100
	v_med3_i32 v195, v194, 0, v195
	v_lshl_add_u32 v202, v195, 2, s20
	v_max_i32_e32 v195, -1, v194
	v_add_u32_e32 v195, 1, v195
	v_min_u32_e32 v195, 0x100, v195
	v_lshl_add_u32 v203, v195, 2, s20
	v_max_i32_e32 v195, -2, v194
	v_add_u32_e32 v195, 2, v195
	v_min_u32_e32 v195, 0x100, v195
	v_lshl_add_u32 v204, v195, 2, s20
	v_max_i32_e32 v195, -3, v194
	v_add_u32_e32 v195, 3, v195
	v_min_u32_e32 v195, 0x100, v195
	v_lshl_add_u32 v205, v195, 2, s20
	v_max_i32_e32 v195, -8, v194
	v_add_u32_e32 v195, 8, v195
	v_min_u32_e32 v195, 0x100, v195
	v_lshl_add_u32 v206, v195, 2, s20
	v_max_i32_e32 v195, -9, v194
	v_add_u32_e32 v195, 9, v195
	v_min_u32_e32 v195, 0x100, v195
	v_lshl_add_u32 v207, v195, 2, s20
	v_max_i32_e32 v195, -10, v194
	v_add_u32_e32 v195, 10, v195
	v_min_u32_e32 v195, 0x100, v195
	v_lshl_add_u32 v208, v195, 2, s20
	v_max_i32_e32 v195, -11, v194
	v_add_u32_e32 v195, 11, v195
	v_min_u32_e32 v195, 0x100, v195
	v_lshl_add_u32 v209, v195, 2, s20
	v_max_i32_e32 v195, -16, v194
	v_max_i32_e32 v196, 0xffffffef, v194
	v_max_i32_e32 v197, 0xffffffee, v194
	v_max_i32_e32 v198, 0xffffffed, v194
	v_max_i32_e32 v199, 0xffffffe8, v194
	v_max_i32_e32 v200, 0xffffffe7, v194
	v_max_i32_e32 v201, 0xffffffe6, v194
	v_add_u32_e32 v195, 16, v195
	v_add_u32_e32 v196, 17, v196
	v_add_u32_e32 v197, 18, v197
	v_add_u32_e32 v198, 19, v198
	v_add_u32_e32 v199, 24, v199
	v_add_u32_e32 v200, 25, v200
	v_add_u32_e32 v201, 26, v201
	v_max_i32_e32 v194, 0xffffffe5, v194
	v_min_u32_e32 v195, 0x100, v195
	v_min_u32_e32 v196, 0x100, v196
	v_min_u32_e32 v197, 0x100, v197
	v_min_u32_e32 v198, 0x100, v198
	v_min_u32_e32 v199, 0x100, v199
	v_min_u32_e32 v200, 0x100, v200
	v_min_u32_e32 v201, 0x100, v201
	v_add_u32_e32 v194, 27, v194
	v_lshl_add_u32 v195, v195, 2, s20
	v_lshl_add_u32 v196, v196, 2, s20
	v_lshl_add_u32 v197, v197, 2, s20
	v_lshl_add_u32 v198, v198, 2, s20
	v_lshl_add_u32 v199, v199, 2, s20
	v_lshl_add_u32 v200, v200, 2, s20
	v_lshl_add_u32 v201, v201, 2, s20
	v_min_u32_e32 v194, 0x100, v194
	v_lshl_add_u32 v211, v194, 2, s20
	ds_read_b32 v194, v195
	ds_read_b32 v195, v196
	ds_read_b32 v196, v197
	ds_read_b32 v197, v198
	ds_read_b32 v198, v199
	ds_read_b32 v199, v200
	ds_read_b32 v200, v201
	ds_read_b32 v201, v211
	ds_read_b32 v202, v202
	ds_read_b32 v203, v203
	ds_read_b32 v204, v204
	ds_read_b32 v205, v205
	ds_read_b32 v206, v206
	ds_read_b32 v207, v207
	ds_read_b32 v208, v208
	ds_read_b32 v209, v209
	s_waitcnt lgkmcnt(0)
	v_pk_add_f32 v[144:145], v[144:145], v[200:201]
	v_pk_add_f32 v[142:143], v[142:143], v[198:199]
	v_pk_add_f32 v[140:141], v[140:141], v[196:197]
	v_pk_add_f32 v[138:139], v[138:139], v[194:195]
	v_pk_add_f32 v[136:137], v[136:137], v[208:209]
	v_pk_add_f32 v[134:135], v[134:135], v[206:207]
	v_pk_add_f32 v[132:133], v[132:133], v[204:205]
	v_pk_add_f32 v[130:131], v[130:131], v[202:203]
	s_mov_b32 s28, 0
	s_branch .LBB0_560
